# XCD-local barrier: acquire invalidate issued by idle wave 1 before the exit workgroup barrier, so the arriving wave's returning atomic is not queued behind it
# baseline (speedup 1.0000x reference)
.Lxw_3:
.LBB0_140:
	s_or_b64 exec, exec, s[0:1]
	v_readlane_b32 s4, v255, 18
	v_readlane_b32 s5, v255, 19
	s_mov_b32 s0, 1
	s_mov_b64 s[6:7], 0
	s_and_b64 vcc, exec, s[4:5]
	s_waitcnt lgkmcnt(0)
	s_cmp_lg_u32 s101, 0
	s_cbranch_scc0 .Lwi_3
	v_readfirstlane_b32 s98, v218
	s_lshr_b32 s98, s98, 6
	s_cmp_eq_u32 s98, 1
	s_cbranch_scc0 .Lwi_3
	buffer_inv sc1
	s_waitcnt vmcnt(0)
.Lwi_3:
	s_barrier
	s_cbranch_vccnz .LBB0_549

.LBB0_194:
	s_mov_b64 s[10:11], exec
	v_mbcnt_lo_u32_b32 v1, s10, 0
	v_mbcnt_hi_u32_b32 v1, s11, v1
	v_cmp_eq_u32_e32 vcc, 0, v1
	s_and_saveexec_b64 s[8:9], vcc
	s_cbranch_execz .LBB0_196
	s_bcnt1_i32_b64 s4, s[10:11]
	v_mov_b32_e32 v3, s4
	v_readlane_b32 s4, v254, 26
	v_readlane_b32 s5, v254, 27
	s_nop 4
	global_atomic_add v3, v177, v3, s[4:5] sc0
	s_cmp_lg_u32 s101, 0
	s_cbranch_scc0 .Lea_0
.Lea_0:
.LBB0_196:
	s_or_b64 exec, exec, s[8:9]
	v_cvt_f32_u32_e32 v4, v2
	s_waitcnt vmcnt(0)
	v_readfirstlane_b32 s4, v3
	v_sub_u32_e32 v3, 0, v2
	v_rcp_iflag_f32_e32 v4, v4
	v_add_u32_e32 v5, s4, v1
	v_mul_f32_e32 v4, 0x4f7ffffe, v4
	v_cvt_u32_f32_e32 v4, v4
	v_mul_lo_u32 v1, v3, v4
	v_mul_hi_u32 v1, v4, v1
	v_add_u32_e32 v1, v4, v1
	v_mul_hi_u32 v1, v5, v1
	v_mul_lo_u32 v3, v1, v2
	v_sub_u32_e32 v3, v5, v3
	v_add_u32_e32 v4, 1, v1
	v_cmp_ge_u32_e32 vcc, v3, v2
	s_nop 1
	v_cndmask_b32_e32 v1, v1, v4, vcc
	v_sub_u32_e32 v4, v3, v2
	v_cndmask_b32_e32 v3, v3, v4, vcc
	v_add_u32_e32 v4, 1, v1
	v_cmp_ge_u32_e32 vcc, v3, v2
	v_add_u32_e32 v3, 1, v5
	s_nop 0
	v_cndmask_b32_e32 v1, v1, v4, vcc
	v_mul_lo_u32 v4, v2, v1
	v_add_u32_e32 v2, v4, v2
	v_cmp_ne_u32_e32 vcc, v3, v2
	s_and_saveexec_b64 s[4:5], vcc
	s_xor_b64 s[8:9], exec, s[4:5]
	s_cbranch_execz .LBB0_210
	v_readlane_b32 s4, v254, 28
	v_readlane_b32 s5, v254, 29
	s_waitcnt lgkmcnt(0)
	s_nop 3
	global_load_dword v0, v177, s[4:5] sc1
	s_waitcnt vmcnt(0)
	v_cmp_eq_u32_e32 vcc, v0, v1
	s_and_saveexec_b64 s[12:13], vcc
	s_cbranch_execz .LBB0_209
	s_mov_b32 s16, 1
	s_mov_b64 s[10:11], 0
	s_branch .LBB0_200

.Lxw_0:
.LBB0_230:
	s_or_b64 exec, exec, s[0:1]
	v_readlane_b32 s56, v253, 32
	s_xor_b64 s[0:1], s[6:7], -1
	v_readlane_b32 s70, v253, 46
	v_readlane_b32 s71, v253, 47
	v_writelane_b32 v255, s0, 18
	s_mov_b64 s[6:7], s[70:71]
	s_waitcnt lgkmcnt(0)
	v_writelane_b32 v255, s1, 19
	s_cmp_lg_u32 s101, 0
	s_cbranch_scc0 .Lwi_0
	v_readfirstlane_b32 s98, v218
	s_lshr_b32 s98, s98, 6
	s_cmp_eq_u32 s98, 1
	s_cbranch_scc0 .Lwi_0
	buffer_inv sc1
	s_waitcnt vmcnt(0)
.Lwi_0:
	s_barrier
	s_add_u32 s8, s6, 0x12d00000
	v_mov_b32_e32 v24, v218
	s_movk_i32 s0, 0x100
	s_addc_u32 s9, s7, 0
	s_and_b32 s98, s2, 7
	s_mul_i32 s98, s98, 0xe00000
	s_add_u32 s8, s8, s98
	s_addc_u32 s9, s9, 0
	v_readlane_b32 s57, v253, 33
	v_cmp_gt_i32_e32 vcc, s0, v24
	v_readlane_b32 s58, v253, 34
	v_readlane_b32 s59, v253, 35
	v_readlane_b32 s60, v253, 36
	v_readlane_b32 s61, v253, 37
	v_readlane_b32 s62, v253, 38
	v_readlane_b32 s63, v253, 39
	v_readlane_b32 s64, v253, 40
	v_readlane_b32 s65, v253, 41
	v_readlane_b32 s66, v253, 42
	v_readlane_b32 s67, v253, 43
	v_readlane_b32 s68, v253, 44
	v_readlane_b32 s69, v253, 45
	s_and_saveexec_b64 s[0:1], vcc
	s_xor_b64 s[0:1], exec, s[0:1]
	s_cbranch_execz .LBB0_243
	v_lshlrev_b32_e32 v0, 3, v24
	v_and_b32_e32 v32, 0x3f8, v0
	v_lshlrev_b32_e32 v20, 2, v32
	global_load_dwordx4 v[0:3], v20, s[22:23] offset:16
	global_load_dwordx4 v[4:7], v20, s[22:23]
	global_load_dwordx4 v[8:11], v20, s[20:21] offset:16
	global_load_dwordx4 v[12:15], v20, s[20:21]
	global_load_dwordx4 v[16:19], v20, s[18:19] offset:16
	s_nop 0
	global_load_dwordx4 v[20:23], v20, s[18:19]
	s_add_u32 s12, s6, 0xa900000
	s_addc_u32 s13, s7, 0
	s_add_u32 s18, s6, 0xe900000
	s_addc_u32 s19, s7, 0
	v_ashrrev_i32_e32 v33, 7, v24
	s_mov_b64 s[20:21], s[2:3]
	s_branch .LBB0_234

.LBB0_344:
	s_mov_b64 s[8:9], exec
	v_mbcnt_lo_u32_b32 v1, s8, 0
	v_mbcnt_hi_u32_b32 v1, s9, v1
	v_cmp_eq_u32_e32 vcc, 0, v1
	s_and_saveexec_b64 s[6:7], vcc
	s_cbranch_execz .LBB0_346
	s_bcnt1_i32_b64 s4, s[8:9]
	v_mov_b32_e32 v3, s4
	v_readlane_b32 s4, v254, 26
	v_readlane_b32 s5, v254, 27
	s_nop 4
	global_atomic_add v3, v177, v3, s[4:5] sc0
	s_cmp_lg_u32 s101, 0
	s_cbranch_scc0 .Lea_1
.Lea_1:
.LBB0_346:
	s_or_b64 exec, exec, s[6:7]
	v_cvt_f32_u32_e32 v4, v2
	s_waitcnt vmcnt(0)
	v_readfirstlane_b32 s4, v3
	v_sub_u32_e32 v3, 0, v2
	v_rcp_iflag_f32_e32 v4, v4
	v_add_u32_e32 v5, s4, v1
	v_mul_f32_e32 v4, 0x4f7ffffe, v4
	v_cvt_u32_f32_e32 v4, v4
	v_mul_lo_u32 v1, v3, v4
	v_mul_hi_u32 v1, v4, v1
	v_add_u32_e32 v1, v4, v1
	v_mul_hi_u32 v1, v5, v1
	v_mul_lo_u32 v3, v1, v2
	v_sub_u32_e32 v3, v5, v3
	v_add_u32_e32 v4, 1, v1
	v_cmp_ge_u32_e32 vcc, v3, v2
	s_nop 1
	v_cndmask_b32_e32 v1, v1, v4, vcc
	v_sub_u32_e32 v4, v3, v2
	v_cndmask_b32_e32 v3, v3, v4, vcc
	v_add_u32_e32 v4, 1, v1
	v_cmp_ge_u32_e32 vcc, v3, v2
	v_add_u32_e32 v3, 1, v5
	s_nop 0
	v_cndmask_b32_e32 v1, v1, v4, vcc
	v_mul_lo_u32 v4, v2, v1
	v_add_u32_e32 v2, v4, v2
	v_cmp_ne_u32_e32 vcc, v3, v2
	s_and_saveexec_b64 s[4:5], vcc
	s_xor_b64 s[6:7], exec, s[4:5]
	s_cbranch_execz .LBB0_360
	v_readlane_b32 s4, v254, 28
	v_readlane_b32 s5, v254, 29
	s_waitcnt lgkmcnt(0)
	s_nop 3
	global_load_dword v0, v177, s[4:5] sc1
	s_waitcnt vmcnt(0)
	v_cmp_eq_u32_e32 vcc, v0, v1
	s_and_saveexec_b64 s[8:9], vcc
	s_cbranch_execz .LBB0_359
	s_mov_b32 s16, 1
	s_mov_b64 s[10:11], 0
	s_branch .LBB0_350

.Lxw_1:
.LBB0_380:
	s_or_b64 exec, exec, s[0:1]
	v_readlane_b32 s56, v253, 32
	v_readlane_b32 s57, v253, 33
	v_readlane_b32 s70, v253, 46
	v_readlane_b32 s71, v253, 47
	v_readlane_b32 s4, v254, 36
	s_mov_b64 s[0:1], s[70:71]
	s_movk_i32 s20, 0x400
	s_waitcnt vmcnt(2)
	v_mov_b32_e32 v12, v218
	v_readlane_b32 s5, v254, 37
	v_readlane_b32 s50, v254, 57
	v_readlane_b32 s56, v254, 59
	s_waitcnt lgkmcnt(0)
	s_cmp_lg_u32 s101, 0
	s_cbranch_scc0 .Lwi_1
	v_readfirstlane_b32 s98, v218
	s_lshr_b32 s98, s98, 6
	s_cmp_eq_u32 s98, 1
	s_cbranch_scc0 .Lwi_1
	buffer_inv sc1
	s_waitcnt vmcnt(0)
.Lwi_1:
	s_barrier
	s_and_b64 vcc, exec, s[4:5]
	v_readfirstlane_b32 s10, v12
	v_readlane_b32 s51, v254, 58
	v_readlane_b32 s57, v254, 60
	v_readlane_b32 s58, v253, 34
	v_readlane_b32 s59, v253, 35
	v_readlane_b32 s60, v253, 36
	v_readlane_b32 s61, v253, 37
	v_readlane_b32 s62, v253, 38
	v_readlane_b32 s63, v253, 39
	v_readlane_b32 s64, v253, 40
	v_readlane_b32 s65, v253, 41
	v_readlane_b32 s66, v253, 42
	v_readlane_b32 s67, v253, 43
	v_readlane_b32 s68, v253, 44
	v_readlane_b32 s69, v253, 45
	s_cbranch_vccz .LBB0_405
	v_lshlrev_b32_e32 v0, 4, v12
	v_add_u32_e32 v1, 0x2000, v0
	v_ashrrev_i32_e32 v2, 31, v1
	v_lshrrev_b32_e32 v2, 22, v2
	v_add_u32_e32 v2, v1, v2
	v_ashrrev_i32_e32 v2, 10, v2
	v_mul_i32_i24_e32 v3, 0x400, v2
	v_sub_u32_e32 v1, v1, v3
	v_lshrrev_b32_e32 v3, 4, v1
	v_bitop3_b32 v1, v3, v1, 32 bitop3:0x6c
	v_ashrrev_i32_e32 v3, 31, v1
	s_add_u32 s16, s0, 0xc00000
	v_lshrrev_b32_e32 v3, 26, v3
	s_addc_u32 s33, s1, 0
	v_add_u32_e32 v3, v1, v3
	v_lshlrev_b32_e32 v5, 3, v2
	s_add_u32 s4, s0, s52
	v_ashrrev_i32_e32 v4, 6, v3
	v_and_b32_e32 v5, -16, v5
	v_lshlrev_b32_e32 v2, 5, v2
	s_addc_u32 s5, s1, 0
	v_add_u32_e32 v5, v4, v5
	v_and_b32_e32 v13, 32, v2
	v_and_b32_e32 v2, 0xc0, v3
	s_add_u32 s34, s4, 0x5400000
	v_and_b32_e32 v4, 3, v4
	s_mov_b32 s4, 0x7fffffe0
	v_lshrrev_b32_e32 v6, 2, v5
	v_lshlrev_b32_e32 v7, 1, v5
	v_sub_u32_e32 v1, v1, v2
	v_and_or_b32 v4, v5, s4, v4
	v_and_b32_e32 v6, 4, v6
	v_and_b32_e32 v7, 24, v7
	v_ashrrev_i16_sdwa v1, v221, sext(v1) dst_sel:DWORD dst_unused:UNUSED_PAD src0_sel:DWORD src1_sel:BYTE_0
	v_or3_b32 v4, v4, v6, v7
	v_bfe_i32 v14, v1, 0, 16
	v_mul_lo_u32 v4, v4, s20
	v_add_u32_e32 v1, v13, v14
	v_mul_lo_u32 v15, v5, s20
	v_add_lshl_u32 v132, v4, v1, 1
	v_add_lshl_u32 v134, v1, v15, 1
	v_bfe_i32 v1, v12, 27, 1
	v_lshrrev_b32_e32 v1, 22, v1
	v_add_u32_e32 v1, v0, v1
	v_and_b32_e32 v1, 0xfffffc00, v1
	v_sub_u32_e32 v0, v0, v1
	v_lshrrev_b32_e32 v1, 4, v0
	v_ashrrev_i32_e32 v3, 31, v12
	v_bitop3_b32 v0, v1, v0, 32 bitop3:0x6c
	v_lshrrev_b32_e32 v3, 26, v3
	v_ashrrev_i32_e32 v1, 31, v0
	v_add_u32_e32 v3, v12, v3
	v_lshrrev_b32_e32 v1, 26, v1
	v_ashrrev_i32_e32 v3, 6, v3
	v_add_u32_e32 v1, v0, v1
	v_lshlrev_b32_e32 v4, 3, v3
	v_ashrrev_i32_e32 v2, 6, v1
	v_and_b32_e32 v4, -16, v4
	s_addc_u32 s35, s5, 0
	s_ashr_i32 s21, s20, 31
	v_add_u32_e32 v4, v2, v4
	v_and_b32_e32 v2, 3, v2
	s_lshl_b64 s[8:9], s[20:21], 9
	v_and_or_b32 v2, v4, s4, v2
	v_readlane_b32 s4, v254, 52
	v_readlane_b32 s13, v255, 6
	s_mul_i32 s4, s8, s4
	s_mul_hi_u32 s5, s8, s13
	s_add_i32 s12, s5, s4
	s_lshr_b64 s[4:5], s[20:21], 23
	v_readlane_b32 s24, v254, 47
	s_mul_i32 s5, s4, s13
	v_readlane_b32 s25, v254, 48
	v_and_b32_e32 v1, 0xc0, v1
	s_add_i32 s12, s12, s5
	s_mul_i32 s5, s8, s25
	s_mul_hi_u32 s18, s8, s24
	s_ashr_i32 s22, s10, 6
	v_lshrrev_b32_e32 v5, 2, v4
	v_lshlrev_b32_e32 v6, 1, v4
	v_sub_u32_e32 v0, v0, v1
	s_add_i32 s5, s18, s5
	s_mul_i32 s4, s4, s24
	s_ashr_i32 s11, s10, 8
	s_lshl_b64 s[6:7], s[20:21], 8
	s_lshl_b32 s36, s22, 10
	v_and_b32_e32 v5, 4, v5
	v_and_b32_e32 v6, 24, v6
	v_lshlrev_b32_e32 v3, 5, v3
	v_ashrrev_i16_sdwa v0, v221, sext(v0) dst_sel:DWORD dst_unused:UNUSED_PAD src0_sel:DWORD src1_sel:BYTE_0
	s_add_i32 s5, s5, s4
	s_mul_i32 s4, s8, s24
	v_or3_b32 v2, v2, v5, v6
	s_waitcnt vmcnt(1)
	v_and_b32_e32 v16, 32, v3
	v_bfe_i32 v17, v0, 0, 16
	s_add_u32 s30, s34, s4
	v_mul_lo_u32 v2, v2, s20
	v_add_u32_e32 v0, v16, v17
	s_addc_u32 s31, s35, s5
	s_add_i32 s37, s36, 0
	v_add_lshl_u32 v176, v2, v0, 1
	s_add_i32 m0, s37, 0x10000
	s_mul_i32 s13, s8, s13
	global_load_lds_dwordx4 v176, s[30:31]
	s_add_i32 m0, s37, 0x12000
	s_add_u32 s4, s30, s6
	global_load_lds_dwordx4 v132, s[30:31]
	s_addc_u32 s5, s31, s7
	s_add_i32 m0, s37, 0x14000
	v_mul_lo_u32 v18, v4, s20
	global_load_lds_dwordx4 v176, s[4:5]
	s_add_i32 m0, s37, 0x16000
	s_add_u32 s28, s16, s13
	v_mov_b32_e32 v133, v177
	s_addc_u32 s29, s33, s12
	s_add_i32 s38, s37, 0x2000
	v_add_lshl_u32 v136, v0, v18, 1
	v_lshl_add_u64 v[4:5], s[4:5], 0, v[176:177]
	v_lshl_add_u64 v[6:7], s[4:5], 0, v[132:133]
	global_load_lds_dwordx4 v132, s[4:5]
	s_mov_b32 m0, s37
	s_add_u32 s4, s28, s6
	global_load_lds_dwordx4 v136, s[28:29]
	s_mov_b32 m0, s38
	s_addc_u32 s5, s29, s7
	s_add_i32 s39, s37, 0x4000
	global_load_lds_dwordx4 v134, s[28:29]
	s_mov_b32 m0, s39
	s_add_i32 s48, s37, 0x6000
	global_load_lds_dwordx4 v136, s[4:5]
	s_mov_b32 m0, s48
	v_mov_b32_e32 v137, v177
	global_load_lds_dwordx4 v134, s[4:5]
	v_mov_b32_e32 v135, v177
	s_cmp_eq_u32 s11, 1
	v_lshl_add_u64 v[0:1], s[30:31], 0, v[176:177]
	v_lshl_add_u64 v[2:3], s[30:31], 0, v[132:133]
	v_lshl_add_u64 v[8:9], s[28:29], 0, v[136:137]
	v_lshl_add_u64 v[10:11], s[28:29], 0, v[134:135]
	s_cselect_b64 s[12:13], -1, 0
	s_cmp_lg_u32 s11, 1
	s_cbranch_scc1 .LBB0_383
	s_barrier

.LBB0_421:
	s_mov_b64 s[8:9], exec
	v_mbcnt_lo_u32_b32 v1, s8, 0
	v_mbcnt_hi_u32_b32 v1, s9, v1
	v_cmp_eq_u32_e32 vcc, 0, v1
	s_and_saveexec_b64 s[6:7], vcc
	s_cbranch_execz .LBB0_423
	s_bcnt1_i32_b64 s4, s[8:9]
	v_mov_b32_e32 v3, s4
	v_readlane_b32 s4, v254, 26
	v_readlane_b32 s5, v254, 27
	s_nop 4
	global_atomic_add v3, v177, v3, s[4:5] sc0
	s_cmp_lg_u32 s101, 0
	s_cbranch_scc0 .Lea_2
.Lea_2:
.LBB0_423:
	s_or_b64 exec, exec, s[6:7]
	v_cvt_f32_u32_e32 v4, v2
	s_waitcnt vmcnt(0)
	v_readfirstlane_b32 s4, v3
	v_sub_u32_e32 v3, 0, v2
	v_rcp_iflag_f32_e32 v4, v4
	v_add_u32_e32 v5, s4, v1
	v_mul_f32_e32 v4, 0x4f7ffffe, v4
	v_cvt_u32_f32_e32 v4, v4
	v_mul_lo_u32 v1, v3, v4
	v_mul_hi_u32 v1, v4, v1
	v_add_u32_e32 v1, v4, v1
	v_mul_hi_u32 v1, v5, v1
	v_mul_lo_u32 v3, v1, v2
	v_sub_u32_e32 v3, v5, v3
	v_add_u32_e32 v4, 1, v1
	v_cmp_ge_u32_e32 vcc, v3, v2
	s_nop 1
	v_cndmask_b32_e32 v1, v1, v4, vcc
	v_sub_u32_e32 v4, v3, v2
	v_cndmask_b32_e32 v3, v3, v4, vcc
	v_add_u32_e32 v4, 1, v1
	v_cmp_ge_u32_e32 vcc, v3, v2
	v_add_u32_e32 v3, 1, v5
	s_nop 0
	v_cndmask_b32_e32 v1, v1, v4, vcc
	v_mul_lo_u32 v4, v2, v1
	v_add_u32_e32 v2, v4, v2
	v_cmp_ne_u32_e32 vcc, v3, v2
	s_and_saveexec_b64 s[4:5], vcc
	s_xor_b64 s[6:7], exec, s[4:5]
	s_cbranch_execz .LBB0_437
	v_readlane_b32 s4, v254, 28
	v_readlane_b32 s5, v254, 29
	s_waitcnt lgkmcnt(0)
	s_nop 3
	global_load_dword v0, v177, s[4:5] sc1
	s_waitcnt vmcnt(0)
	v_cmp_eq_u32_e32 vcc, v0, v1
	s_and_saveexec_b64 s[8:9], vcc
	s_cbranch_execz .LBB0_436
	s_mov_b32 s16, 1
	s_mov_b64 s[10:11], 0
	s_branch .LBB0_427

.Lxw_2:
.LBB0_457:
	s_or_b64 exec, exec, s[0:1]
	v_readlane_b32 s56, v253, 32
	v_readlane_b32 s68, v253, 44
	v_readlane_b32 s69, v253, 45
	v_readlane_b32 s70, v253, 46
	v_readlane_b32 s71, v253, 47
	v_readlane_b32 s4, v253, 50
	s_mov_b64 s[0:1], s[70:71]
	s_movk_i32 s20, 0xb00
	v_mov_b32_e32 v18, v218
	v_readlane_b32 s5, v253, 51
	v_readlane_b32 s68, v254, 57
	v_readlane_b32 s70, v254, 59
	s_waitcnt lgkmcnt(0)
	s_cmp_lg_u32 s101, 0
	s_cbranch_scc0 .Lwi_2
	v_readfirstlane_b32 s98, v218
	s_lshr_b32 s98, s98, 6
	s_cmp_eq_u32 s98, 1
	s_cbranch_scc0 .Lwi_2
	buffer_inv sc1
	s_waitcnt vmcnt(0)
.Lwi_2:
	s_barrier
	s_and_b64 vcc, exec, s[4:5]
	v_readfirstlane_b32 s10, v18
	v_readlane_b32 s69, v254, 58
	v_readlane_b32 s71, v254, 60
	v_readlane_b32 s57, v253, 33
	v_readlane_b32 s58, v253, 34
	v_readlane_b32 s59, v253, 35
	v_readlane_b32 s60, v253, 36
	v_readlane_b32 s61, v253, 37
	v_readlane_b32 s62, v253, 38
	v_readlane_b32 s63, v253, 39
	v_readlane_b32 s64, v253, 40
	v_readlane_b32 s65, v253, 41
	v_readlane_b32 s66, v253, 42
	v_readlane_b32 s67, v253, 43
	s_cbranch_vccz .LBB0_498
	v_lshlrev_b32_e32 v0, 4, v18
	v_add_u32_e32 v1, 0x2000, v0
	v_ashrrev_i32_e32 v2, 31, v1
	v_lshrrev_b32_e32 v2, 22, v2
	v_add_u32_e32 v2, v1, v2
	v_ashrrev_i32_e32 v2, 10, v2
	v_mul_i32_i24_e32 v3, 0x400, v2
	v_sub_u32_e32 v1, v1, v3
	v_lshrrev_b32_e32 v3, 4, v1
	v_bitop3_b32 v1, v3, v1, 32 bitop3:0x6c
	v_ashrrev_i32_e32 v3, 31, v1
	s_add_u32 s33, s0, 0x12d00000
	v_lshrrev_b32_e32 v3, 26, v3
	s_addc_u32 s34, s1, 0
	v_add_u32_e32 v3, v1, v3
	v_lshlrev_b32_e32 v5, 3, v2
	s_add_u32 s4, s0, s52
	v_ashrrev_i32_e32 v4, 6, v3
	v_and_b32_e32 v5, -16, v5
	v_lshlrev_b32_e32 v2, 5, v2
	s_addc_u32 s5, s1, 0
	v_add_u32_e32 v5, v4, v5
	v_and_b32_e32 v12, 32, v2
	v_and_b32_e32 v2, 0xc0, v3
	s_add_u32 s35, s4, 0x5f00000
	v_and_b32_e32 v4, 3, v4
	s_mov_b32 s4, 0x7fffffe0
	v_lshrrev_b32_e32 v6, 2, v5
	v_lshlrev_b32_e32 v7, 1, v5
	v_sub_u32_e32 v1, v1, v2
	v_and_or_b32 v4, v5, s4, v4
	v_and_b32_e32 v6, 4, v6
	v_and_b32_e32 v7, 24, v7
	v_ashrrev_i16_sdwa v1, v221, sext(v1) dst_sel:DWORD dst_unused:UNUSED_PAD src0_sel:DWORD src1_sel:BYTE_0
	v_or3_b32 v4, v4, v6, v7
	v_bfe_i32 v13, v1, 0, 16
	v_mul_lo_u32 v4, v4, s20
	v_add_u32_e32 v1, v12, v13
	v_mul_lo_u32 v14, v5, s20
	v_add_lshl_u32 v156, v4, v1, 1
	v_add_lshl_u32 v158, v1, v14, 1
	v_bfe_i32 v1, v18, 27, 1
	v_lshrrev_b32_e32 v1, 22, v1
	v_add_u32_e32 v1, v0, v1
	v_and_b32_e32 v1, 0xfffffc00, v1
	v_sub_u32_e32 v0, v0, v1
	v_lshrrev_b32_e32 v1, 4, v0
	v_ashrrev_i32_e32 v3, 31, v18
	v_bitop3_b32 v0, v1, v0, 32 bitop3:0x6c
	v_lshrrev_b32_e32 v3, 26, v3
	v_ashrrev_i32_e32 v1, 31, v0
	v_add_u32_e32 v3, v18, v3
	v_lshrrev_b32_e32 v1, 26, v1
	v_ashrrev_i32_e32 v3, 6, v3
	v_add_u32_e32 v1, v0, v1
	v_lshlrev_b32_e32 v4, 3, v3
	v_ashrrev_i32_e32 v2, 6, v1
	v_and_b32_e32 v4, -16, v4
	s_addc_u32 s36, s5, 0
	s_ashr_i32 s21, s20, 31
	v_add_u32_e32 v4, v2, v4
	v_and_b32_e32 v2, 3, v2
	s_lshl_b64 s[8:9], s[20:21], 9
	v_and_or_b32 v2, v4, s4, v2
	v_readlane_b32 s4, v254, 53
	s_mul_i32 s4, s8, s4
	s_mul_hi_u32 s5, s8, s95
	s_add_i32 s12, s5, s4
	s_lshr_b64 s[4:5], s[20:21], 23
	v_readlane_b32 s22, v254, 50
	s_mul_i32 s5, s4, s95
	v_readlane_b32 s23, v254, 51
	v_and_b32_e32 v1, 0xc0, v1
	s_add_i32 s12, s12, s5
	s_mul_i32 s5, s8, s23
	s_mul_hi_u32 s18, s8, s22
	s_ashr_i32 s16, s10, 6
	v_lshrrev_b32_e32 v5, 2, v4
	v_lshlrev_b32_e32 v6, 1, v4
	v_sub_u32_e32 v0, v0, v1
	s_add_i32 s5, s18, s5
	s_mul_i32 s4, s4, s22
	s_ashr_i32 s11, s10, 8
	s_lshl_b64 s[6:7], s[20:21], 8
	s_lshl_b32 s37, s16, 10
	v_and_b32_e32 v5, 4, v5
	v_and_b32_e32 v6, 24, v6
	v_lshlrev_b32_e32 v3, 5, v3
	v_ashrrev_i16_sdwa v0, v221, sext(v0) dst_sel:DWORD dst_unused:UNUSED_PAD src0_sel:DWORD src1_sel:BYTE_0
	s_add_i32 s5, s5, s4
	s_mul_i32 s4, s8, s22
	v_or3_b32 v2, v2, v5, v6
	v_and_b32_e32 v15, 32, v3
	v_bfe_i32 v16, v0, 0, 16
	s_add_u32 s30, s35, s4
	v_mul_lo_u32 v2, v2, s20
	v_add_u32_e32 v0, v15, v16
	s_addc_u32 s31, s36, s5
	s_add_i32 s38, s37, 0
	v_add_lshl_u32 v176, v2, v0, 1
	s_add_i32 m0, s38, 0x10000
	s_mul_i32 s13, s8, s95
	global_load_lds_dwordx4 v176, s[30:31]
	s_add_i32 m0, s38, 0x12000
	s_add_u32 s4, s30, s6
	global_load_lds_dwordx4 v156, s[30:31]
	s_addc_u32 s5, s31, s7
	s_add_i32 m0, s38, 0x14000
	v_mul_lo_u32 v17, v4, s20
	global_load_lds_dwordx4 v176, s[4:5]
	s_add_i32 m0, s38, 0x16000
	s_add_u32 s28, s33, s13
	v_mov_b32_e32 v157, v177
	s_addc_u32 s29, s34, s12
	s_add_i32 s39, s38, 0x2000
	v_add_lshl_u32 v160, v0, v17, 1
	v_lshl_add_u64 v[4:5], s[4:5], 0, v[176:177]
	v_lshl_add_u64 v[6:7], s[4:5], 0, v[156:157]
	global_load_lds_dwordx4 v156, s[4:5]
	s_mov_b32 m0, s38
	s_add_u32 s4, s28, s6
	global_load_lds_dwordx4 v160, s[28:29]
	s_mov_b32 m0, s39
	s_addc_u32 s5, s29, s7
	s_add_i32 s48, s38, 0x4000
	global_load_lds_dwordx4 v158, s[28:29]
	s_mov_b32 m0, s48
	s_add_i32 s49, s38, 0x6000
	global_load_lds_dwordx4 v160, s[4:5]
	s_mov_b32 m0, s49
	v_mov_b32_e32 v161, v177
	global_load_lds_dwordx4 v158, s[4:5]
	v_mov_b32_e32 v159, v177
	s_cmp_eq_u32 s11, 1
	v_lshl_add_u64 v[0:1], s[30:31], 0, v[176:177]
	v_lshl_add_u64 v[2:3], s[30:31], 0, v[156:157]
	v_lshl_add_u64 v[8:9], s[28:29], 0, v[160:161]
	v_lshl_add_u64 v[10:11], s[28:29], 0, v[158:159]
	s_cselect_b64 s[12:13], -1, 0
	s_cmp_lg_u32 s11, 1
	s_cbranch_scc1 .LBB0_460
	s_barrier

.LBB0_514:
	s_mov_b64 s[8:9], exec
	v_mbcnt_lo_u32_b32 v1, s8, 0
	v_mbcnt_hi_u32_b32 v1, s9, v1
	v_cmp_eq_u32_e32 vcc, 0, v1
	s_and_saveexec_b64 s[6:7], vcc
	s_cbranch_execz .LBB0_516
	s_bcnt1_i32_b64 s4, s[8:9]
	v_mov_b32_e32 v3, s4
	v_readlane_b32 s4, v254, 26
	v_readlane_b32 s5, v254, 27
	s_nop 4
	global_atomic_add v3, v177, v3, s[4:5] sc0
	s_cmp_lg_u32 s101, 0
	s_cbranch_scc0 .Lea_3
.Lea_3:
.LBB0_516:
	s_or_b64 exec, exec, s[6:7]
	v_cvt_f32_u32_e32 v4, v2
	s_waitcnt vmcnt(0)
	v_readfirstlane_b32 s4, v3
	v_sub_u32_e32 v3, 0, v2
	v_rcp_iflag_f32_e32 v4, v4
	v_add_u32_e32 v5, s4, v1
	v_mul_f32_e32 v4, 0x4f7ffffe, v4
	v_cvt_u32_f32_e32 v4, v4
	v_mul_lo_u32 v1, v3, v4
	v_mul_hi_u32 v1, v4, v1
	v_add_u32_e32 v1, v4, v1
	v_mul_hi_u32 v1, v5, v1
	v_mul_lo_u32 v3, v1, v2
	v_sub_u32_e32 v3, v5, v3
	v_add_u32_e32 v4, 1, v1
	v_cmp_ge_u32_e32 vcc, v3, v2
	s_nop 1
	v_cndmask_b32_e32 v1, v1, v4, vcc
	v_sub_u32_e32 v4, v3, v2
	v_cndmask_b32_e32 v3, v3, v4, vcc
	v_add_u32_e32 v4, 1, v1
	v_cmp_ge_u32_e32 vcc, v3, v2
	v_add_u32_e32 v3, 1, v5
	s_nop 0
	v_cndmask_b32_e32 v1, v1, v4, vcc
	v_mul_lo_u32 v4, v2, v1
	v_add_u32_e32 v2, v4, v2
	v_cmp_ne_u32_e32 vcc, v3, v2
	s_and_saveexec_b64 s[4:5], vcc
	s_xor_b64 s[6:7], exec, s[4:5]
	s_cbranch_execz .LBB0_530
	v_readlane_b32 s4, v254, 28
	v_readlane_b32 s5, v254, 29
	s_waitcnt lgkmcnt(0)
	s_nop 3
	global_load_dword v0, v177, s[4:5] sc1
	s_waitcnt vmcnt(0)
	v_cmp_eq_u32_e32 vcc, v0, v1
	s_and_saveexec_b64 s[8:9], vcc
	s_cbranch_execz .LBB0_529
	s_mov_b32 s16, 1
	s_mov_b64 s[10:11], 0
	s_branch .LBB0_520

.Lxw_9:
.LBB0_551:
	s_or_b64 exec, exec, s[0:1]
	s_mov_b64 s[0:1], 1
	v_writelane_b32 v253, s0, 54
	s_mov_b64 s[40:41], 0
	s_waitcnt lgkmcnt(0)
	v_writelane_b32 v253, s1, 55
	s_cmp_lg_u32 s101, 0
	s_cbranch_scc0 .Lwi_9
	v_readfirstlane_b32 s98, v218
	s_lshr_b32 s98, s98, 6
	s_cmp_eq_u32 s98, 1
	s_cbranch_scc0 .Lwi_9
	buffer_inv sc1
	s_waitcnt vmcnt(0)
.Lwi_9:
	s_barrier
	v_readlane_b32 s0, v253, 52
	v_readlane_b32 s1, v253, 53
	s_and_b64 vcc, exec, s[0:1]
	s_cbranch_vccnz .LBB0_1299

.LBB0_743:
	s_mov_b64 s[8:9], exec
	v_mbcnt_lo_u32_b32 v1, s8, 0
	v_mbcnt_hi_u32_b32 v1, s9, v1
	v_cmp_eq_u32_e32 vcc, 0, v1
	s_and_saveexec_b64 s[6:7], vcc
	s_cbranch_execz .LBB0_745
	s_bcnt1_i32_b64 s4, s[8:9]
	v_readlane_b32 s8, v254, 26
	v_mov_b32_e32 v3, s4
	v_readlane_b32 s9, v254, 27
	s_nop 4
	global_atomic_add v3, v181, v3, s[8:9] sc0
	s_cmp_lg_u32 s101, 0
	s_cbranch_scc0 .Lea_4
.Lea_4:
.LBB0_745:
	s_or_b64 exec, exec, s[6:7]
	v_cvt_f32_u32_e32 v4, v2
	s_waitcnt vmcnt(0)
	v_readfirstlane_b32 s4, v3
	v_sub_u32_e32 v3, 0, v2
	v_rcp_iflag_f32_e32 v4, v4
	v_add_u32_e32 v5, s4, v1
	v_mul_f32_e32 v4, 0x4f7ffffe, v4
	v_cvt_u32_f32_e32 v4, v4
	v_mul_lo_u32 v1, v3, v4
	v_mul_hi_u32 v1, v4, v1
	v_add_u32_e32 v1, v4, v1
	v_mul_hi_u32 v1, v5, v1
	v_mul_lo_u32 v3, v1, v2
	v_sub_u32_e32 v3, v5, v3
	v_add_u32_e32 v4, 1, v1
	v_cmp_ge_u32_e32 vcc, v3, v2
	s_nop 1
	v_cndmask_b32_e32 v1, v1, v4, vcc
	v_sub_u32_e32 v4, v3, v2
	v_cndmask_b32_e32 v3, v3, v4, vcc
	v_add_u32_e32 v4, 1, v1
	v_cmp_ge_u32_e32 vcc, v3, v2
	v_add_u32_e32 v3, 1, v5
	s_nop 0
	v_cndmask_b32_e32 v1, v1, v4, vcc
	v_mul_lo_u32 v4, v2, v1
	v_add_u32_e32 v2, v4, v2
	v_cmp_ne_u32_e32 vcc, v3, v2
	s_and_saveexec_b64 s[6:7], vcc
	s_xor_b64 s[6:7], exec, s[6:7]
	s_cbranch_execz .LBB0_759
	v_readlane_b32 s8, v254, 28
	v_readlane_b32 s9, v254, 29
	s_waitcnt lgkmcnt(0)
	s_nop 3
	global_load_dword v0, v181, s[8:9] sc1
	s_waitcnt vmcnt(0)
	v_cmp_eq_u32_e32 vcc, v0, v1
	s_and_saveexec_b64 s[8:9], vcc
	s_cbranch_execz .LBB0_758
	s_mov_b32 s4, 1
	s_mov_b64 s[10:11], 0
	s_branch .LBB0_749

.Lxw_4:
.LBB0_779:
	s_or_b64 exec, exec, s[0:1]
	s_andn2_b64 vcc, exec, s[40:41]
	s_waitcnt lgkmcnt(0)
	s_cmp_lg_u32 s101, 0
	s_cbranch_scc0 .Lwi_4
	v_readfirstlane_b32 s98, v218
	s_lshr_b32 s98, s98, 6
	s_cmp_eq_u32 s98, 1
	s_cbranch_scc0 .Lwi_4
	buffer_inv sc1
	s_waitcnt vmcnt(0)
.Lwi_4:
	s_barrier
	s_cbranch_vccnz .LBB0_830
	v_readlane_b32 s16, v253, 32
	v_readlane_b32 s18, v253, 34
	v_readlane_b32 s19, v253, 35
	v_readlane_b32 s20, v253, 36
	v_readlane_b32 s30, v253, 46
	v_readlane_b32 s31, v253, 47
	v_readlane_b32 s0, v255, 20
	s_mov_b64 s[18:19], s[30:31]
	s_movk_i32 s20, 0x100
	v_mov_b32_e32 v12, v218
	v_readlane_b32 s1, v255, 21
	s_and_b64 vcc, exec, s[0:1]
	v_readfirstlane_b32 s10, v12
	v_readlane_b32 s17, v253, 33
	v_readlane_b32 s21, v253, 37
	v_readlane_b32 s22, v253, 38
	v_readlane_b32 s23, v253, 39
	v_readlane_b32 s24, v253, 40
	v_readlane_b32 s25, v253, 41
	v_readlane_b32 s26, v253, 42
	v_readlane_b32 s27, v253, 43
	v_readlane_b32 s28, v253, 44
	v_readlane_b32 s29, v253, 45
	s_cbranch_vccnz .LBB0_805
	v_lshlrev_b32_e32 v0, 4, v12
	v_add_u32_e32 v1, 0x2000, v0
	v_ashrrev_i32_e32 v2, 31, v1
	v_lshrrev_b32_e32 v2, 22, v2
	v_add_u32_e32 v2, v1, v2
	v_ashrrev_i32_e32 v2, 10, v2
	v_mul_i32_i24_e32 v3, 0x400, v2
	v_sub_u32_e32 v1, v1, v3
	v_lshrrev_b32_e32 v3, 4, v1
	v_bitop3_b32 v1, v3, v1, 32 bitop3:0x6c
	v_ashrrev_i32_e32 v3, 31, v1
	v_lshrrev_b32_e32 v3, 26, v3
	v_add_u32_e32 v3, v1, v3
	v_lshlrev_b32_e32 v5, 3, v2
	v_ashrrev_i32_e32 v4, 6, v3
	v_and_b32_e32 v5, -16, v5
	v_lshlrev_b32_e32 v2, 5, v2
	v_add_u32_e32 v5, v4, v5
	v_and_b32_e32 v13, 32, v2
	v_and_b32_e32 v2, 0xc0, v3
	v_and_b32_e32 v4, 3, v4
	s_mov_b32 s8, 0x7fffffe0
	v_lshrrev_b32_e32 v6, 2, v5
	v_lshlrev_b32_e32 v7, 1, v5
	v_sub_u32_e32 v1, v1, v2
	v_and_or_b32 v4, v5, s8, v4
	v_and_b32_e32 v6, 4, v6
	v_and_b32_e32 v7, 24, v7
	v_ashrrev_i16_sdwa v1, v205, sext(v1) dst_sel:DWORD dst_unused:UNUSED_PAD src0_sel:DWORD src1_sel:BYTE_0
	v_or3_b32 v4, v4, v6, v7
	v_bfe_i32 v14, v1, 0, 16
	v_mul_lo_u32 v4, v4, s20
	v_add_u32_e32 v1, v13, v14
	v_mul_lo_u32 v15, v5, s20
	v_add_lshl_u32 v128, v4, v1, 1
	v_add_lshl_u32 v130, v1, v15, 1
	v_bfe_i32 v1, v12, 27, 1
	v_lshrrev_b32_e32 v1, 22, v1
	v_add_u32_e32 v1, v0, v1
	v_and_b32_e32 v1, 0xfffffc00, v1
	v_sub_u32_e32 v0, v0, v1
	v_lshrrev_b32_e32 v1, 4, v0
	v_ashrrev_i32_e32 v3, 31, v12
	v_bitop3_b32 v0, v1, v0, 32 bitop3:0x6c
	v_lshrrev_b32_e32 v3, 26, v3
	v_ashrrev_i32_e32 v1, 31, v0
	v_add_u32_e32 v3, v12, v3
	s_add_u32 s4, s18, 0x13900000
	v_lshrrev_b32_e32 v1, 26, v1
	v_ashrrev_i32_e32 v3, 6, v3
	s_addc_u32 s33, s19, 0
	s_and_b32 s98, s2, 7
	s_mul_i32 s98, s98, 0x1400000
	s_add_u32 s4, s4, s98
	s_addc_u32 s33, s33, 0
	v_add_u32_e32 v1, v0, v1
	v_lshlrev_b32_e32 v4, 3, v3
	s_add_u32 s34, s18, 0x7f00000
	v_ashrrev_i32_e32 v2, 6, v1
	v_and_b32_e32 v4, -16, v4
	s_addc_u32 s35, s19, 0
	s_ashr_i32 s21, s20, 31
	v_add_u32_e32 v4, v2, v4
	v_and_b32_e32 v2, 3, v2
	s_lshl_b64 s[6:7], s[20:21], 9
	v_and_or_b32 v2, v4, s8, v2
	v_readlane_b32 s8, v254, 53
	s_mul_i32 s8, s6, s8
	s_mul_hi_u32 s9, s6, s95
	s_add_i32 s14, s9, s8
	s_lshr_b64 s[8:9], s[20:21], 23
	v_readlane_b32 s24, v254, 50
	s_mul_i32 s9, s8, s95
	v_readlane_b32 s25, v254, 51
	v_and_b32_e32 v1, 0xc0, v1
	s_add_i32 s14, s14, s9
	s_mul_i32 s9, s6, s25
	s_mul_hi_u32 s16, s6, s24
	s_ashr_i32 s11, s10, 6
	v_lshrrev_b32_e32 v5, 2, v4
	v_lshlrev_b32_e32 v6, 1, v4
	v_sub_u32_e32 v0, v0, v1
	s_add_i32 s9, s16, s9
	s_mul_i32 s8, s8, s24
	s_ashr_i32 s22, s10, 8
	s_lshl_b64 s[0:1], s[20:21], 8
	s_lshl_b32 s36, s11, 10
	v_and_b32_e32 v5, 4, v5
	v_and_b32_e32 v6, 24, v6
	v_lshlrev_b32_e32 v3, 5, v3
	v_ashrrev_i16_sdwa v0, v205, sext(v0) dst_sel:DWORD dst_unused:UNUSED_PAD src0_sel:DWORD src1_sel:BYTE_0
	s_add_i32 s9, s9, s8
	s_mul_i32 s8, s6, s24
	v_or3_b32 v2, v2, v5, v6
	v_and_b32_e32 v16, 32, v3
	v_bfe_i32 v17, v0, 0, 16
	s_add_u32 s30, s34, s8
	v_mul_lo_u32 v2, v2, s20
	v_add_u32_e32 v0, v16, v17
	s_addc_u32 s31, s35, s9
	s_add_i32 s37, s36, 0
	v_add_lshl_u32 v132, v2, v0, 1
	s_add_i32 m0, s37, 0x10000
	s_mul_i32 s15, s6, s95
	global_load_lds_dwordx4 v132, s[30:31]
	s_add_i32 m0, s37, 0x12000
	s_add_u32 s8, s30, s0
	global_load_lds_dwordx4 v128, s[30:31]
	s_addc_u32 s9, s31, s1
	s_add_i32 m0, s37, 0x14000
	v_mul_lo_u32 v18, v4, s20
	global_load_lds_dwordx4 v132, s[8:9]
	s_add_i32 m0, s37, 0x16000
	s_add_u32 s16, s4, s15
	v_mov_b32_e32 v133, v181
	v_mov_b32_e32 v129, v181
	s_addc_u32 s17, s33, s14
	s_add_i32 s38, s37, 0x2000
	v_add_lshl_u32 v134, v0, v18, 1
	v_lshl_add_u64 v[4:5], s[8:9], 0, v[132:133]
	v_lshl_add_u64 v[6:7], s[8:9], 0, v[128:129]
	global_load_lds_dwordx4 v128, s[8:9]
	s_mov_b32 m0, s37
	s_add_u32 s8, s16, s0
	global_load_lds_dwordx4 v134, s[16:17]
	s_mov_b32 m0, s38
	s_addc_u32 s9, s17, s1
	s_add_i32 s39, s37, 0x4000
	global_load_lds_dwordx4 v130, s[16:17]
	s_mov_b32 m0, s39
	s_add_i32 s44, s37, 0x6000
	global_load_lds_dwordx4 v134, s[8:9]
	s_mov_b32 m0, s44
	v_mov_b32_e32 v135, v181
	global_load_lds_dwordx4 v130, s[8:9]
	v_mov_b32_e32 v131, v181
	s_cmp_eq_u32 s22, 1
	v_lshl_add_u64 v[0:1], s[30:31], 0, v[132:133]
	v_lshl_add_u64 v[2:3], s[30:31], 0, v[128:129]
	v_lshl_add_u64 v[8:9], s[16:17], 0, v[134:135]
	v_lshl_add_u64 v[10:11], s[16:17], 0, v[130:131]
	s_cselect_b64 s[8:9], -1, 0
	s_cmp_lg_u32 s22, 1
	s_cbranch_scc1 .LBB0_783
	s_barrier

.LBB0_899:
	s_mov_b64 s[8:9], exec
	v_mbcnt_lo_u32_b32 v1, s8, 0
	v_mbcnt_hi_u32_b32 v1, s9, v1
	v_cmp_eq_u32_e32 vcc, 0, v1
	s_and_saveexec_b64 s[6:7], vcc
	s_cbranch_execz .LBB0_901
	s_bcnt1_i32_b64 s4, s[8:9]
	v_readlane_b32 s8, v254, 26
	v_mov_b32_e32 v3, s4
	v_readlane_b32 s9, v254, 27
	s_nop 4
	global_atomic_add v3, v181, v3, s[8:9] sc0
	s_cmp_lg_u32 s101, 0
	s_cbranch_scc0 .Lea_5
.Lea_5:
.LBB0_901:
	s_or_b64 exec, exec, s[6:7]
	v_cvt_f32_u32_e32 v4, v2
	s_waitcnt vmcnt(0)
	v_readfirstlane_b32 s4, v3
	v_sub_u32_e32 v3, 0, v2
	v_rcp_iflag_f32_e32 v4, v4
	v_add_u32_e32 v5, s4, v1
	v_mul_f32_e32 v4, 0x4f7ffffe, v4
	v_cvt_u32_f32_e32 v4, v4
	v_mul_lo_u32 v1, v3, v4
	v_mul_hi_u32 v1, v4, v1
	v_add_u32_e32 v1, v4, v1
	v_mul_hi_u32 v1, v5, v1
	v_mul_lo_u32 v3, v1, v2
	v_sub_u32_e32 v3, v5, v3
	v_add_u32_e32 v4, 1, v1
	v_cmp_ge_u32_e32 vcc, v3, v2
	s_nop 1
	v_cndmask_b32_e32 v1, v1, v4, vcc
	v_sub_u32_e32 v4, v3, v2
	v_cndmask_b32_e32 v3, v3, v4, vcc
	v_add_u32_e32 v4, 1, v1
	v_cmp_ge_u32_e32 vcc, v3, v2
	v_add_u32_e32 v3, 1, v5
	s_nop 0
	v_cndmask_b32_e32 v1, v1, v4, vcc
	v_mul_lo_u32 v4, v2, v1
	v_add_u32_e32 v2, v4, v2
	v_cmp_ne_u32_e32 vcc, v3, v2
	s_and_saveexec_b64 s[6:7], vcc
	s_xor_b64 s[6:7], exec, s[6:7]
	s_cbranch_execz .LBB0_915
	v_readlane_b32 s8, v254, 28
	v_readlane_b32 s9, v254, 29
	s_waitcnt lgkmcnt(0)
	s_nop 3
	global_load_dword v0, v181, s[8:9] sc1
	s_waitcnt vmcnt(0)
	v_cmp_eq_u32_e32 vcc, v0, v1
	s_and_saveexec_b64 s[8:9], vcc
	s_cbranch_execz .LBB0_914
	s_mov_b32 s4, 1
	s_mov_b64 s[10:11], 0
	s_branch .LBB0_905

.Lxw_5:
.LBB0_935:
	s_or_b64 exec, exec, s[0:1]
	v_readlane_b32 s16, v253, 32
	v_readlane_b32 s0, v254, 42
	v_readlane_b32 s30, v253, 46
	v_readlane_b32 s31, v253, 47
	v_readlane_b32 s1, v254, 43
	s_mov_b64 s[6:7], s[30:31]
	s_andn2_b64 vcc, exec, s[0:1]
	s_waitcnt lgkmcnt(0)
	s_cmp_lg_u32 s101, 0
	s_cbranch_scc0 .Lwi_5
	v_readfirstlane_b32 s98, v218
	s_lshr_b32 s98, s98, 6
	s_cmp_eq_u32 s98, 1
	s_cbranch_scc0 .Lwi_5
	buffer_inv sc1
	s_waitcnt vmcnt(0)
.Lwi_5:
	s_barrier
	v_readlane_b32 s17, v253, 33
	v_readlane_b32 s18, v253, 34
	v_readlane_b32 s19, v253, 35
	v_readlane_b32 s20, v253, 36
	v_readlane_b32 s21, v253, 37
	v_readlane_b32 s22, v253, 38
	v_readlane_b32 s23, v253, 39
	v_readlane_b32 s24, v253, 40
	v_readlane_b32 s25, v253, 41
	v_readlane_b32 s26, v253, 42
	v_readlane_b32 s27, v253, 43
	v_readlane_b32 s28, v253, 44
	v_readlane_b32 s29, v253, 45
	s_cbranch_vccnz .LBB0_983
	s_add_u32 s8, s6, 0x12d00000
	s_addc_u32 s9, s7, 0
	s_and_b32 s98, s2, 7
	s_mul_i32 s98, s98, 0xa00000
	s_add_u32 s8, s8, s98
	s_addc_u32 s9, s9, 0
	s_add_u32 s4, s6, 0xa900000
	s_addc_u32 s33, s7, 0
	s_add_u32 s44, s6, 0x12900000
	s_addc_u32 s45, s7, 0
	s_add_u32 s46, s6, 0xe900000
	s_addc_u32 s47, s7, 0
	s_add_u32 s14, s6, 0x13900000
	s_addc_u32 s15, s7, 0
	s_and_b32 s98, s2, 7
	s_mul_i32 s98, s98, 0xe00000
	s_add_u32 s14, s14, s98
	s_addc_u32 s15, s15, 0
	v_readlane_b32 s48, v255, 10
	s_and_b32 s100, s2, 7
	s_lshl_b32 s100, s100, 5
	s_add_i32 s48, s48, s100
	s_add_i32 s100, s48, 64
	s_branch .LBB0_938

.LBB0_999:
	s_mov_b64 s[8:9], exec
	v_mbcnt_lo_u32_b32 v1, s8, 0
	v_mbcnt_hi_u32_b32 v1, s9, v1
	v_cmp_eq_u32_e32 vcc, 0, v1
	s_and_saveexec_b64 s[6:7], vcc
	s_cbranch_execz .LBB0_1001
	s_bcnt1_i32_b64 s4, s[8:9]
	v_readlane_b32 s8, v254, 26
	v_mov_b32_e32 v3, s4
	v_readlane_b32 s9, v254, 27
	s_nop 4
	global_atomic_add v3, v181, v3, s[8:9] sc0
	s_cmp_lg_u32 s101, 0
	s_cbranch_scc0 .Lea_6
.Lea_6:
.LBB0_1001:
	s_or_b64 exec, exec, s[6:7]
	v_cvt_f32_u32_e32 v4, v2
	s_waitcnt vmcnt(0)
	v_readfirstlane_b32 s4, v3
	v_sub_u32_e32 v3, 0, v2
	v_rcp_iflag_f32_e32 v4, v4
	v_add_u32_e32 v5, s4, v1
	v_mul_f32_e32 v4, 0x4f7ffffe, v4
	v_cvt_u32_f32_e32 v4, v4
	v_mul_lo_u32 v1, v3, v4
	v_mul_hi_u32 v1, v4, v1
	v_add_u32_e32 v1, v4, v1
	v_mul_hi_u32 v1, v5, v1
	v_mul_lo_u32 v3, v1, v2
	v_sub_u32_e32 v3, v5, v3
	v_add_u32_e32 v4, 1, v1
	v_cmp_ge_u32_e32 vcc, v3, v2
	s_nop 1
	v_cndmask_b32_e32 v1, v1, v4, vcc
	v_sub_u32_e32 v4, v3, v2
	v_cndmask_b32_e32 v3, v3, v4, vcc
	v_add_u32_e32 v4, 1, v1
	v_cmp_ge_u32_e32 vcc, v3, v2
	v_add_u32_e32 v3, 1, v5
	s_nop 0
	v_cndmask_b32_e32 v1, v1, v4, vcc
	v_mul_lo_u32 v4, v2, v1
	v_add_u32_e32 v2, v4, v2
	v_cmp_ne_u32_e32 vcc, v3, v2
	s_and_saveexec_b64 s[6:7], vcc
	s_xor_b64 s[6:7], exec, s[6:7]
	s_cbranch_execz .LBB0_1015
	v_readlane_b32 s8, v254, 28
	v_readlane_b32 s9, v254, 29
	s_waitcnt lgkmcnt(0)
	s_nop 3
	global_load_dword v0, v181, s[8:9] sc1
	s_waitcnt vmcnt(0)
	v_cmp_eq_u32_e32 vcc, v0, v1
	s_and_saveexec_b64 s[8:9], vcc
	s_cbranch_execz .LBB0_1014
	s_mov_b32 s4, 1
	s_mov_b64 s[10:11], 0
	s_branch .LBB0_1005

.Lxw_6:
.LBB0_1035:
	s_or_b64 exec, exec, s[0:1]
	v_readlane_b32 s16, v253, 32
	v_readlane_b32 s30, v253, 46
	v_readlane_b32 s31, v253, 47
	v_readlane_b32 s6, v255, 20
	s_mov_b64 s[0:1], s[30:31]
	s_movk_i32 s16, 0x400
	v_mov_b32_e32 v18, v218
	v_readlane_b32 s7, v255, 21
	s_waitcnt lgkmcnt(0)
	s_cmp_lg_u32 s101, 0
	s_cbranch_scc0 .Lwi_6
	v_readfirstlane_b32 s98, v218
	s_lshr_b32 s98, s98, 6
	s_cmp_eq_u32 s98, 1
	s_cbranch_scc0 .Lwi_6
	buffer_inv sc1
	s_waitcnt vmcnt(0)
.Lwi_6:
	s_barrier
	s_and_b64 vcc, exec, s[6:7]
	v_readfirstlane_b32 s10, v18
	v_readlane_b32 s17, v253, 33
	v_readlane_b32 s18, v253, 34
	v_readlane_b32 s19, v253, 35
	v_readlane_b32 s20, v253, 36
	v_readlane_b32 s21, v253, 37
	v_readlane_b32 s22, v253, 38
	v_readlane_b32 s23, v253, 39
	v_readlane_b32 s24, v253, 40
	v_readlane_b32 s25, v253, 41
	v_readlane_b32 s26, v253, 42
	v_readlane_b32 s27, v253, 43
	v_readlane_b32 s28, v253, 44
	v_readlane_b32 s29, v253, 45
	s_cbranch_vccnz .LBB0_1076
	v_lshlrev_b32_e32 v0, 4, v18
	v_add_u32_e32 v1, 0x2000, v0
	v_ashrrev_i32_e32 v2, 31, v1
	v_lshrrev_b32_e32 v2, 22, v2
	v_add_u32_e32 v2, v1, v2
	v_ashrrev_i32_e32 v2, 10, v2
	v_mul_i32_i24_e32 v3, 0x400, v2
	v_sub_u32_e32 v1, v1, v3
	v_lshrrev_b32_e32 v3, 4, v1
	v_bitop3_b32 v1, v3, v1, 32 bitop3:0x6c
	v_ashrrev_i32_e32 v3, 31, v1
	v_lshrrev_b32_e32 v3, 26, v3
	v_add_u32_e32 v3, v1, v3
	v_lshlrev_b32_e32 v5, 3, v2
	v_ashrrev_i32_e32 v4, 6, v3
	v_and_b32_e32 v5, -16, v5
	v_lshlrev_b32_e32 v2, 5, v2
	v_add_u32_e32 v5, v4, v5
	v_and_b32_e32 v12, 32, v2
	v_and_b32_e32 v2, 0xc0, v3
	v_and_b32_e32 v4, 3, v4
	s_mov_b32 s14, 0x7fffffe0
	v_lshrrev_b32_e32 v6, 2, v5
	v_lshlrev_b32_e32 v7, 1, v5
	v_sub_u32_e32 v1, v1, v2
	v_and_or_b32 v4, v5, s14, v4
	v_and_b32_e32 v6, 4, v6
	v_and_b32_e32 v7, 24, v7
	v_ashrrev_i16_sdwa v1, v205, sext(v1) dst_sel:DWORD dst_unused:UNUSED_PAD src0_sel:DWORD src1_sel:BYTE_0
	v_or3_b32 v4, v4, v6, v7
	v_bfe_i32 v13, v1, 0, 16
	v_mul_lo_u32 v4, v4, s16
	v_add_u32_e32 v1, v12, v13
	v_mul_lo_u32 v14, v5, s16
	v_add_lshl_u32 v156, v4, v1, 1
	v_add_lshl_u32 v158, v1, v14, 1
	v_bfe_i32 v1, v18, 27, 1
	v_lshrrev_b32_e32 v1, 22, v1
	v_add_u32_e32 v1, v0, v1
	v_and_b32_e32 v1, 0xfffffc00, v1
	v_sub_u32_e32 v0, v0, v1
	v_readlane_b32 s6, v253, 54
	v_lshrrev_b32_e32 v1, 4, v0
	v_ashrrev_i32_e32 v3, 31, v18
	s_add_u32 s4, s0, 0x13900000
	v_readlane_b32 s7, v253, 55
	v_bitop3_b32 v0, v1, v0, 32 bitop3:0x6c
	v_lshrrev_b32_e32 v3, 26, v3
	s_addc_u32 s33, s1, 0
	s_and_b32 s98, s2, 7
	s_mul_i32 s98, s98, 0xe00000
	s_add_u32 s4, s4, s98
	s_addc_u32 s33, s33, 0
	s_lshl_b64 s[6:7], s[6:7], 21
	v_ashrrev_i32_e32 v1, 31, v0
	v_add_u32_e32 v3, v18, v3
	s_add_u32 s6, s0, s6
	v_lshrrev_b32_e32 v1, 26, v1
	v_ashrrev_i32_e32 v3, 6, v3
	s_addc_u32 s7, s1, s7
	v_add_u32_e32 v1, v0, v1
	v_lshlrev_b32_e32 v4, 3, v3
	s_add_u32 s34, s6, 0x8340000
	v_ashrrev_i32_e32 v2, 6, v1
	v_and_b32_e32 v4, -16, v4
	s_addc_u32 s35, s7, 0
	s_ashr_i32 s17, s16, 31
	v_add_u32_e32 v4, v2, v4
	v_and_b32_e32 v2, 3, v2
	s_lshl_b64 s[8:9], s[16:17], 9
	v_and_or_b32 v2, v4, s14, v2
	v_readlane_b32 s14, v254, 53
	s_mul_i32 s14, s8, s14
	s_mul_hi_u32 s15, s8, s95
	s_add_i32 s18, s15, s14
	s_lshr_b64 s[14:15], s[16:17], 23
	v_readlane_b32 s22, v254, 50
	s_mul_i32 s15, s14, s95
	v_readlane_b32 s23, v254, 51
	v_and_b32_e32 v1, 0xc0, v1
	s_add_i32 s18, s18, s15
	s_mul_i32 s15, s8, s23
	s_mul_hi_u32 s21, s8, s22
	s_ashr_i32 s20, s10, 6
	v_lshrrev_b32_e32 v5, 2, v4
	v_lshlrev_b32_e32 v6, 1, v4
	v_sub_u32_e32 v0, v0, v1
	s_add_i32 s15, s21, s15
	s_mul_i32 s14, s14, s22
	s_ashr_i32 s11, s10, 8
	s_lshl_b64 s[6:7], s[16:17], 8
	s_lshl_b32 s36, s20, 10
	v_and_b32_e32 v5, 4, v5
	v_and_b32_e32 v6, 24, v6
	v_lshlrev_b32_e32 v3, 5, v3
	v_ashrrev_i16_sdwa v0, v205, sext(v0) dst_sel:DWORD dst_unused:UNUSED_PAD src0_sel:DWORD src1_sel:BYTE_0
	s_add_i32 s15, s15, s14
	s_mul_i32 s14, s8, s22
	v_or3_b32 v2, v2, v5, v6
	v_and_b32_e32 v15, 32, v3
	v_bfe_i32 v16, v0, 0, 16
	s_add_u32 s30, s34, s14
	v_mul_lo_u32 v2, v2, s16
	v_add_u32_e32 v0, v15, v16
	s_addc_u32 s31, s35, s15
	s_add_i32 s37, s36, 0
	v_add_lshl_u32 v180, v2, v0, 1
	s_add_i32 m0, s37, 0x10000
	s_mul_i32 s19, s8, s95
	global_load_lds_dwordx4 v180, s[30:31]
	s_add_i32 m0, s37, 0x12000
	s_add_u32 s14, s30, s6
	global_load_lds_dwordx4 v156, s[30:31]
	s_addc_u32 s15, s31, s7
	s_add_i32 m0, s37, 0x14000
	v_mul_lo_u32 v17, v4, s16
	global_load_lds_dwordx4 v180, s[14:15]
	s_add_i32 m0, s37, 0x16000
	s_add_u32 s28, s4, s19
	v_mov_b32_e32 v157, v181
	s_addc_u32 s29, s33, s18
	s_add_i32 s38, s37, 0x2000
	s_waitcnt vmcnt(0)
	v_add_lshl_u32 v160, v0, v17, 1
	v_lshl_add_u64 v[4:5], s[14:15], 0, v[180:181]
	v_lshl_add_u64 v[6:7], s[14:15], 0, v[156:157]
	global_load_lds_dwordx4 v156, s[14:15]
	s_mov_b32 m0, s37
	s_add_u32 s14, s28, s6
	global_load_lds_dwordx4 v160, s[28:29]
	s_mov_b32 m0, s38
	s_addc_u32 s15, s29, s7
	s_add_i32 s39, s37, 0x4000
	global_load_lds_dwordx4 v158, s[28:29]
	s_mov_b32 m0, s39
	s_add_i32 s46, s37, 0x6000
	global_load_lds_dwordx4 v160, s[14:15]
	s_mov_b32 m0, s46
	v_mov_b32_e32 v161, v181
	global_load_lds_dwordx4 v158, s[14:15]
	v_mov_b32_e32 v159, v181
	s_cmp_eq_u32 s11, 1
	v_mov_b32_e32 v240, 1
	v_lshl_add_u64 v[0:1], s[30:31], 0, v[180:181]
	v_lshl_add_u64 v[2:3], s[30:31], 0, v[156:157]
	v_lshl_add_u64 v[8:9], s[28:29], 0, v[160:161]
	v_lshl_add_u64 v[10:11], s[28:29], 0, v[158:159]
	s_cselect_b64 s[14:15], -1, 0
	s_cmp_lg_u32 s11, 1
	s_cbranch_scc1 .LBB0_1038
	s_barrier

.LBB0_1092:
	s_mov_b64 s[8:9], exec
	v_mbcnt_lo_u32_b32 v1, s8, 0
	v_mbcnt_hi_u32_b32 v1, s9, v1
	v_cmp_eq_u32_e32 vcc, 0, v1
	s_and_saveexec_b64 s[6:7], vcc
	s_cbranch_execz .LBB0_1094
	s_bcnt1_i32_b64 s4, s[8:9]
	v_readlane_b32 s8, v254, 26
	v_mov_b32_e32 v3, s4
	v_readlane_b32 s9, v254, 27
	s_nop 4
	global_atomic_add v3, v181, v3, s[8:9] sc0
	s_cmp_lg_u32 s101, 0
	s_cbranch_scc0 .Lea_7
.Lea_7:
.LBB0_1094:
	s_or_b64 exec, exec, s[6:7]
	v_cvt_f32_u32_e32 v4, v2
	s_waitcnt vmcnt(0)
	v_readfirstlane_b32 s4, v3
	v_sub_u32_e32 v3, 0, v2
	v_rcp_iflag_f32_e32 v4, v4
	v_add_u32_e32 v5, s4, v1
	v_mul_f32_e32 v4, 0x4f7ffffe, v4
	v_cvt_u32_f32_e32 v4, v4
	v_mul_lo_u32 v1, v3, v4
	v_mul_hi_u32 v1, v4, v1
	v_add_u32_e32 v1, v4, v1
	v_mul_hi_u32 v1, v5, v1
	v_mul_lo_u32 v3, v1, v2
	v_sub_u32_e32 v3, v5, v3
	v_add_u32_e32 v4, 1, v1
	v_cmp_ge_u32_e32 vcc, v3, v2
	s_nop 1
	v_cndmask_b32_e32 v1, v1, v4, vcc
	v_sub_u32_e32 v4, v3, v2
	v_cndmask_b32_e32 v3, v3, v4, vcc
	v_add_u32_e32 v4, 1, v1
	v_cmp_ge_u32_e32 vcc, v3, v2
	v_add_u32_e32 v3, 1, v5
	s_nop 0
	v_cndmask_b32_e32 v1, v1, v4, vcc
	v_mul_lo_u32 v4, v2, v1
	v_add_u32_e32 v2, v4, v2
	v_cmp_ne_u32_e32 vcc, v3, v2
	s_and_saveexec_b64 s[6:7], vcc
	s_xor_b64 s[6:7], exec, s[6:7]
	s_cbranch_execz .LBB0_1108
	v_readlane_b32 s8, v254, 28
	v_readlane_b32 s9, v254, 29
	s_waitcnt lgkmcnt(0)
	s_nop 3
	global_load_dword v0, v181, s[8:9] sc1
	s_waitcnt vmcnt(0)
	v_cmp_eq_u32_e32 vcc, v0, v1
	s_and_saveexec_b64 s[8:9], vcc
	s_cbranch_execz .LBB0_1107
	s_mov_b32 s4, 1
	s_mov_b64 s[10:11], 0
	s_branch .LBB0_1098

.Lxw_7:
.LBB0_1128:
	s_or_b64 exec, exec, s[0:1]
	v_readlane_b32 s16, v253, 32
	v_readlane_b32 s30, v253, 46
	v_readlane_b32 s31, v253, 47
	v_readlane_b32 s6, v254, 36
	s_mov_b64 s[0:1], s[30:31]
	s_movk_i32 s16, 0x400
	v_mov_b32_e32 v12, v218
	v_readlane_b32 s7, v254, 37
	s_waitcnt lgkmcnt(0)
	s_cmp_lg_u32 s101, 0
	s_cbranch_scc0 .Lwi_7
	v_readfirstlane_b32 s98, v218
	s_lshr_b32 s98, s98, 6
	s_cmp_eq_u32 s98, 1
	s_cbranch_scc0 .Lwi_7
	buffer_inv sc1
	s_waitcnt vmcnt(0)
.Lwi_7:
	s_barrier
	s_andn2_b64 vcc, exec, s[6:7]
	v_readfirstlane_b32 s10, v12
	v_readlane_b32 s17, v253, 33
	v_readlane_b32 s18, v253, 34
	v_readlane_b32 s19, v253, 35
	v_readlane_b32 s20, v253, 36
	v_readlane_b32 s21, v253, 37
	v_readlane_b32 s22, v253, 38
	v_readlane_b32 s23, v253, 39
	v_readlane_b32 s24, v253, 40
	v_readlane_b32 s25, v253, 41
	v_readlane_b32 s26, v253, 42
	v_readlane_b32 s27, v253, 43
	v_readlane_b32 s28, v253, 44
	v_readlane_b32 s29, v253, 45
	s_cbranch_vccnz .LBB0_1154
	v_lshlrev_b32_e32 v0, 4, v12
	v_add_u32_e32 v1, 0x2000, v0
	v_ashrrev_i32_e32 v2, 31, v1
	v_lshrrev_b32_e32 v2, 22, v2
	v_add_u32_e32 v2, v1, v2
	v_ashrrev_i32_e32 v2, 10, v2
	v_mul_i32_i24_e32 v3, 0x400, v2
	v_sub_u32_e32 v1, v1, v3
	v_lshrrev_b32_e32 v3, 4, v1
	v_bitop3_b32 v1, v3, v1, 32 bitop3:0x6c
	v_ashrrev_i32_e32 v3, 31, v1
	v_lshrrev_b32_e32 v3, 26, v3
	v_add_u32_e32 v3, v1, v3
	v_lshlrev_b32_e32 v5, 3, v2
	v_ashrrev_i32_e32 v4, 6, v3
	v_and_b32_e32 v5, -16, v5
	v_lshlrev_b32_e32 v2, 5, v2
	v_add_u32_e32 v5, v4, v5
	v_and_b32_e32 v13, 32, v2
	v_and_b32_e32 v2, 0xc0, v3
	v_and_b32_e32 v4, 3, v4
	s_mov_b32 s14, 0x7fffffe0
	v_lshrrev_b32_e32 v6, 2, v5
	v_lshlrev_b32_e32 v7, 1, v5
	v_sub_u32_e32 v1, v1, v2
	v_and_or_b32 v4, v5, s14, v4
	v_and_b32_e32 v6, 4, v6
	v_and_b32_e32 v7, 24, v7
	v_ashrrev_i16_sdwa v1, v205, sext(v1) dst_sel:DWORD dst_unused:UNUSED_PAD src0_sel:DWORD src1_sel:BYTE_0
	v_or3_b32 v4, v4, v6, v7
	v_bfe_i32 v14, v1, 0, 16
	v_mul_lo_u32 v4, v4, s16
	v_add_u32_e32 v1, v13, v14
	v_mul_lo_u32 v15, v5, s16
	v_add_lshl_u32 v132, v4, v1, 1
	v_add_lshl_u32 v134, v1, v15, 1
	v_bfe_i32 v1, v12, 27, 1
	v_lshrrev_b32_e32 v1, 22, v1
	v_add_u32_e32 v1, v0, v1
	v_and_b32_e32 v1, 0xfffffc00, v1
	v_sub_u32_e32 v0, v0, v1
	v_lshrrev_b32_e32 v1, 4, v0
	v_ashrrev_i32_e32 v3, 31, v12
	s_add_u32 s4, s0, 0xc00000
	v_readlane_b32 s6, v253, 54
	v_bitop3_b32 v0, v1, v0, 32 bitop3:0x6c
	v_lshrrev_b32_e32 v3, 26, v3
	s_addc_u32 s33, s1, 0
	s_mul_i32 s6, s6, 0xb00000
	v_ashrrev_i32_e32 v1, 31, v0
	v_add_u32_e32 v3, v12, v3
	v_readlane_b32 s7, v253, 55
	s_add_u32 s6, s0, s6
	v_lshrrev_b32_e32 v1, 26, v1
	v_ashrrev_i32_e32 v3, 6, v3
	s_addc_u32 s7, s1, 0
	v_add_u32_e32 v1, v0, v1
	v_lshlrev_b32_e32 v4, 3, v3
	s_add_u32 s34, s6, 0x8740000
	v_ashrrev_i32_e32 v2, 6, v1
	v_and_b32_e32 v4, -16, v4
	s_addc_u32 s35, s7, 0
	s_ashr_i32 s17, s16, 31
	v_add_u32_e32 v4, v2, v4
	v_and_b32_e32 v2, 3, v2
	s_lshl_b64 s[8:9], s[16:17], 9
	v_and_or_b32 v2, v4, s14, v2
	v_readlane_b32 s14, v254, 52
	v_readlane_b32 s19, v255, 6
	s_mul_i32 s14, s8, s14
	s_mul_hi_u32 s15, s8, s19
	s_add_i32 s18, s15, s14
	s_lshr_b64 s[14:15], s[16:17], 23
	v_readlane_b32 s22, v254, 47
	s_mul_i32 s15, s14, s19
	v_readlane_b32 s23, v254, 48
	v_and_b32_e32 v1, 0xc0, v1
	s_add_i32 s18, s18, s15
	s_mul_i32 s15, s8, s23
	s_mul_hi_u32 s21, s8, s22
	s_ashr_i32 s20, s10, 6
	v_lshrrev_b32_e32 v5, 2, v4
	v_lshlrev_b32_e32 v6, 1, v4
	v_sub_u32_e32 v0, v0, v1
	s_add_i32 s15, s21, s15
	s_mul_i32 s14, s14, s22
	s_ashr_i32 s11, s10, 8
	s_lshl_b64 s[6:7], s[16:17], 8
	s_lshl_b32 s36, s20, 10
	v_and_b32_e32 v5, 4, v5
	v_and_b32_e32 v6, 24, v6
	v_lshlrev_b32_e32 v3, 5, v3
	v_ashrrev_i16_sdwa v0, v205, sext(v0) dst_sel:DWORD dst_unused:UNUSED_PAD src0_sel:DWORD src1_sel:BYTE_0
	s_add_i32 s15, s15, s14
	s_mul_i32 s14, s8, s22
	v_or3_b32 v2, v2, v5, v6
	v_and_b32_e32 v16, 32, v3
	v_bfe_i32 v17, v0, 0, 16
	s_add_u32 s30, s34, s14
	v_mul_lo_u32 v2, v2, s16
	v_add_u32_e32 v0, v16, v17
	s_addc_u32 s31, s35, s15
	s_add_i32 s37, s36, 0
	v_add_lshl_u32 v180, v2, v0, 1
	s_add_i32 m0, s37, 0x10000
	s_mul_i32 s19, s8, s19
	global_load_lds_dwordx4 v180, s[30:31]
	s_add_i32 m0, s37, 0x12000
	s_add_u32 s14, s30, s6
	global_load_lds_dwordx4 v132, s[30:31]
	s_addc_u32 s15, s31, s7
	s_add_i32 m0, s37, 0x14000
	v_mul_lo_u32 v18, v4, s16
	global_load_lds_dwordx4 v180, s[14:15]
	s_add_i32 m0, s37, 0x16000
	s_add_u32 s28, s4, s19
	v_mov_b32_e32 v133, v181
	s_addc_u32 s29, s33, s18
	s_add_i32 s38, s37, 0x2000
	v_add_lshl_u32 v136, v0, v18, 1
	v_lshl_add_u64 v[4:5], s[14:15], 0, v[180:181]
	v_lshl_add_u64 v[6:7], s[14:15], 0, v[132:133]
	global_load_lds_dwordx4 v132, s[14:15]
	s_mov_b32 m0, s37
	s_add_u32 s14, s28, s6
	global_load_lds_dwordx4 v136, s[28:29]
	s_mov_b32 m0, s38
	s_addc_u32 s15, s29, s7
	s_add_i32 s39, s37, 0x4000
	global_load_lds_dwordx4 v134, s[28:29]
	s_mov_b32 m0, s39
	s_add_i32 s46, s37, 0x6000
	global_load_lds_dwordx4 v136, s[14:15]
	s_mov_b32 m0, s46
	v_mov_b32_e32 v137, v181
	global_load_lds_dwordx4 v134, s[14:15]
	v_mov_b32_e32 v135, v181
	s_cmp_eq_u32 s11, 1
	v_lshl_add_u64 v[0:1], s[30:31], 0, v[180:181]
	v_lshl_add_u64 v[2:3], s[30:31], 0, v[132:133]
	v_lshl_add_u64 v[8:9], s[28:29], 0, v[136:137]
	v_lshl_add_u64 v[10:11], s[28:29], 0, v[134:135]
	s_cselect_b64 s[14:15], -1, 0
	s_cmp_lg_u32 s11, 1
	s_cbranch_scc1 .LBB0_1131
	s_barrier

.LBB0_1170:
	s_mov_b64 s[8:9], exec
	v_mbcnt_lo_u32_b32 v1, s8, 0
	v_mbcnt_hi_u32_b32 v1, s9, v1
	v_cmp_eq_u32_e32 vcc, 0, v1
	s_and_saveexec_b64 s[6:7], vcc
	s_cbranch_execz .LBB0_1172
	s_bcnt1_i32_b64 s4, s[8:9]
	v_readlane_b32 s8, v254, 26
	v_mov_b32_e32 v3, s4
	v_readlane_b32 s9, v254, 27
	s_nop 4
	global_atomic_add v3, v181, v3, s[8:9] sc0
	s_cmp_lg_u32 s101, 0
	s_cbranch_scc0 .Lea_8
.Lea_8:
.LBB0_1172:
	s_or_b64 exec, exec, s[6:7]
	v_cvt_f32_u32_e32 v4, v2
	s_waitcnt vmcnt(0)
	v_readfirstlane_b32 s4, v3
	v_sub_u32_e32 v3, 0, v2
	v_rcp_iflag_f32_e32 v4, v4
	v_add_u32_e32 v5, s4, v1
	v_mul_f32_e32 v4, 0x4f7ffffe, v4
	v_cvt_u32_f32_e32 v4, v4
	v_mul_lo_u32 v1, v3, v4
	v_mul_hi_u32 v1, v4, v1
	v_add_u32_e32 v1, v4, v1
	v_mul_hi_u32 v1, v5, v1
	v_mul_lo_u32 v3, v1, v2
	v_sub_u32_e32 v3, v5, v3
	v_add_u32_e32 v4, 1, v1
	v_cmp_ge_u32_e32 vcc, v3, v2
	s_nop 1
	v_cndmask_b32_e32 v1, v1, v4, vcc
	v_sub_u32_e32 v4, v3, v2
	v_cndmask_b32_e32 v3, v3, v4, vcc
	v_add_u32_e32 v4, 1, v1
	v_cmp_ge_u32_e32 vcc, v3, v2
	v_add_u32_e32 v3, 1, v5
	s_nop 0
	v_cndmask_b32_e32 v1, v1, v4, vcc
	v_mul_lo_u32 v4, v2, v1
	v_add_u32_e32 v2, v4, v2
	v_cmp_ne_u32_e32 vcc, v3, v2
	s_and_saveexec_b64 s[6:7], vcc
	s_xor_b64 s[6:7], exec, s[6:7]
	s_cbranch_execz .LBB0_1186
	v_readlane_b32 s8, v254, 28
	v_readlane_b32 s9, v254, 29
	s_waitcnt lgkmcnt(0)
	s_nop 3
	global_load_dword v0, v181, s[8:9] sc1
	s_waitcnt vmcnt(0)
	v_cmp_eq_u32_e32 vcc, v0, v1
	s_and_saveexec_b64 s[8:9], vcc
	s_cbranch_execz .LBB0_1185
	s_mov_b32 s4, 1
	s_mov_b64 s[10:11], 0
	s_branch .LBB0_1176

.Lxw_8:
.LBB0_1206:
	s_or_b64 exec, exec, s[0:1]
	v_readlane_b32 s16, v253, 32
	v_readlane_b32 s18, v253, 34
	v_readlane_b32 s30, v253, 46
	v_readlane_b32 s31, v253, 47
	v_readlane_b32 s6, v255, 20
	s_mov_b64 s[0:1], s[30:31]
	s_movk_i32 s18, 0xb00
	v_mov_b32_e32 v18, v218
	v_readlane_b32 s7, v255, 21
	s_waitcnt lgkmcnt(0)
	s_cmp_lg_u32 s101, 0
	s_cbranch_scc0 .Lwi_8
	v_readfirstlane_b32 s98, v218
	s_lshr_b32 s98, s98, 6
	s_cmp_eq_u32 s98, 1
	s_cbranch_scc0 .Lwi_8
	buffer_inv sc1
	s_waitcnt vmcnt(0)
.Lwi_8:
	s_barrier
	s_and_b64 vcc, exec, s[6:7]
	v_readfirstlane_b32 s10, v18
	v_readlane_b32 s17, v253, 33
	v_readlane_b32 s19, v253, 35
	v_readlane_b32 s20, v253, 36
	v_readlane_b32 s21, v253, 37
	v_readlane_b32 s22, v253, 38
	v_readlane_b32 s23, v253, 39
	v_readlane_b32 s24, v253, 40
	v_readlane_b32 s25, v253, 41
	v_readlane_b32 s26, v253, 42
	v_readlane_b32 s27, v253, 43
	v_readlane_b32 s28, v253, 44
	v_readlane_b32 s29, v253, 45
	s_cbranch_vccnz .LBB0_1248
	v_lshlrev_b32_e32 v0, 4, v18
	v_add_u32_e32 v1, 0x2000, v0
	v_ashrrev_i32_e32 v2, 31, v1
	v_lshrrev_b32_e32 v2, 22, v2
	v_add_u32_e32 v2, v1, v2
	v_ashrrev_i32_e32 v2, 10, v2
	v_mul_i32_i24_e32 v3, 0x400, v2
	v_sub_u32_e32 v1, v1, v3
	v_lshrrev_b32_e32 v3, 4, v1
	v_bitop3_b32 v1, v3, v1, 32 bitop3:0x6c
	v_ashrrev_i32_e32 v3, 31, v1
	v_lshrrev_b32_e32 v3, 26, v3
	v_add_u32_e32 v3, v1, v3
	v_lshlrev_b32_e32 v5, 3, v2
	v_ashrrev_i32_e32 v4, 6, v3
	v_and_b32_e32 v5, -16, v5
	v_lshlrev_b32_e32 v2, 5, v2
	v_add_u32_e32 v5, v4, v5
	v_and_b32_e32 v12, 32, v2
	v_and_b32_e32 v2, 0xc0, v3
	v_and_b32_e32 v4, 3, v4
	s_mov_b32 s14, 0x7fffffe0
	v_lshrrev_b32_e32 v6, 2, v5
	v_lshlrev_b32_e32 v7, 1, v5
	v_sub_u32_e32 v1, v1, v2
	v_and_or_b32 v4, v5, s14, v4
	v_and_b32_e32 v6, 4, v6
	v_and_b32_e32 v7, 24, v7
	v_ashrrev_i16_sdwa v1, v205, sext(v1) dst_sel:DWORD dst_unused:UNUSED_PAD src0_sel:DWORD src1_sel:BYTE_0
	v_or3_b32 v4, v4, v6, v7
	v_bfe_i32 v13, v1, 0, 16
	v_mul_lo_u32 v4, v4, s18
	v_add_u32_e32 v1, v12, v13
	v_mul_lo_u32 v14, v5, s18
	v_add_lshl_u32 v156, v4, v1, 1
	v_add_lshl_u32 v158, v1, v14, 1
	v_bfe_i32 v1, v18, 27, 1
	v_lshrrev_b32_e32 v1, 22, v1
	v_add_u32_e32 v1, v0, v1
	v_and_b32_e32 v1, 0xfffffc00, v1
	v_sub_u32_e32 v0, v0, v1
	v_lshrrev_b32_e32 v1, 4, v0
	v_ashrrev_i32_e32 v3, 31, v18
	s_add_u32 s4, s0, 0x12d00000
	v_readlane_b32 s6, v253, 54
	v_bitop3_b32 v0, v1, v0, 32 bitop3:0x6c
	v_lshrrev_b32_e32 v3, 26, v3
	s_addc_u32 s30, s1, 0
	s_mul_i32 s6, s6, 0x580000
	v_ashrrev_i32_e32 v1, 31, v0
	v_add_u32_e32 v3, v18, v3
	v_readlane_b32 s7, v253, 55
	s_add_u32 s6, s0, s6
	v_lshrrev_b32_e32 v1, 26, v1
	v_ashrrev_i32_e32 v3, 6, v3
	s_addc_u32 s7, s1, 0
	v_add_u32_e32 v1, v0, v1
	v_lshlrev_b32_e32 v4, 3, v3
	s_add_u32 s31, s6, 0x9d40000
	v_ashrrev_i32_e32 v2, 6, v1
	v_and_b32_e32 v4, -16, v4
	s_addc_u32 s33, s7, 0
	s_ashr_i32 s19, s18, 31
	v_add_u32_e32 v4, v2, v4
	v_and_b32_e32 v2, 3, v2
	s_lshl_b64 s[8:9], s[18:19], 9
	v_and_or_b32 v2, v4, s14, v2
	v_readlane_b32 s14, v254, 53
	s_mul_i32 s14, s8, s14
	s_mul_hi_u32 s15, s8, s95
	s_add_i32 s16, s15, s14
	s_lshr_b64 s[14:15], s[18:19], 23
	v_readlane_b32 s22, v254, 50
	s_mul_i32 s15, s14, s95
	v_readlane_b32 s23, v254, 51
	v_and_b32_e32 v1, 0xc0, v1
	s_add_i32 s16, s16, s15
	s_mul_i32 s15, s8, s23
	s_mul_hi_u32 s21, s8, s22
	s_ashr_i32 s20, s10, 6
	v_lshrrev_b32_e32 v5, 2, v4
	v_lshlrev_b32_e32 v6, 1, v4
	v_sub_u32_e32 v0, v0, v1
	s_add_i32 s15, s21, s15
	s_mul_i32 s14, s14, s22
	s_ashr_i32 s11, s10, 8
	s_lshl_b64 s[6:7], s[18:19], 8
	s_lshl_b32 s34, s20, 10
	v_and_b32_e32 v5, 4, v5
	v_and_b32_e32 v6, 24, v6
	v_lshlrev_b32_e32 v3, 5, v3
	v_ashrrev_i16_sdwa v0, v205, sext(v0) dst_sel:DWORD dst_unused:UNUSED_PAD src0_sel:DWORD src1_sel:BYTE_0
	s_add_i32 s15, s15, s14
	s_mul_i32 s14, s8, s22
	v_or3_b32 v2, v2, v5, v6
	v_and_b32_e32 v15, 32, v3
	v_bfe_i32 v16, v0, 0, 16
	s_add_u32 s28, s31, s14
	v_mul_lo_u32 v2, v2, s18
	v_add_u32_e32 v0, v15, v16
	s_addc_u32 s29, s33, s15
	s_add_i32 s35, s34, 0
	v_add_lshl_u32 v180, v2, v0, 1
	s_add_i32 m0, s35, 0x10000
	s_mul_i32 s17, s8, s95
	global_load_lds_dwordx4 v180, s[28:29]
	s_add_i32 m0, s35, 0x12000
	s_add_u32 s14, s28, s6
	global_load_lds_dwordx4 v156, s[28:29]
	s_addc_u32 s15, s29, s7
	s_add_i32 m0, s35, 0x14000
	v_mul_lo_u32 v17, v4, s18
	global_load_lds_dwordx4 v180, s[14:15]
	s_add_i32 m0, s35, 0x16000
	s_add_u32 s26, s4, s17
	v_mov_b32_e32 v157, v181
	s_addc_u32 s27, s30, s16
	s_add_i32 s36, s35, 0x2000
	s_waitcnt vmcnt(0)
	v_add_lshl_u32 v160, v0, v17, 1
	v_lshl_add_u64 v[4:5], s[14:15], 0, v[180:181]
	v_lshl_add_u64 v[6:7], s[14:15], 0, v[156:157]
	global_load_lds_dwordx4 v156, s[14:15]
	s_mov_b32 m0, s35
	s_add_u32 s14, s26, s6
	global_load_lds_dwordx4 v160, s[26:27]
	s_mov_b32 m0, s36
	s_addc_u32 s15, s27, s7
	s_add_i32 s37, s35, 0x4000
	global_load_lds_dwordx4 v158, s[26:27]
	s_mov_b32 m0, s37
	s_add_i32 s38, s35, 0x6000
	global_load_lds_dwordx4 v160, s[14:15]
	s_mov_b32 m0, s38
	v_mov_b32_e32 v161, v181
	global_load_lds_dwordx4 v158, s[14:15]
	v_mov_b32_e32 v159, v181
	s_cmp_eq_u32 s11, 1
	v_mov_b32_e32 v240, 1
	v_lshl_add_u64 v[0:1], s[28:29], 0, v[180:181]
	v_lshl_add_u64 v[2:3], s[28:29], 0, v[156:157]
	v_lshl_add_u64 v[8:9], s[26:27], 0, v[160:161]
	v_lshl_add_u64 v[10:11], s[26:27], 0, v[158:159]
	s_cselect_b64 s[14:15], -1, 0
	s_cmp_lg_u32 s11, 1
	s_cbranch_scc1 .LBB0_1209
	s_barrier

.LBB0_1264:
	s_mov_b64 s[8:9], exec
	v_mbcnt_lo_u32_b32 v1, s8, 0
	v_mbcnt_hi_u32_b32 v1, s9, v1
	v_cmp_eq_u32_e32 vcc, 0, v1
	s_and_saveexec_b64 s[6:7], vcc
	s_cbranch_execz .LBB0_1266
	s_bcnt1_i32_b64 s4, s[8:9]
	v_readlane_b32 s8, v254, 26
	v_mov_b32_e32 v3, s4
	v_readlane_b32 s9, v254, 27
	s_nop 4
	global_atomic_add v3, v181, v3, s[8:9] sc0
	s_cmp_lg_u32 s101, 0
	s_cbranch_scc0 .Lea_9
.Lea_9:
.LBB0_1266:
	s_or_b64 exec, exec, s[6:7]
	v_cvt_f32_u32_e32 v4, v2
	s_waitcnt vmcnt(0)
	v_readfirstlane_b32 s4, v3
	v_sub_u32_e32 v3, 0, v2
	v_rcp_iflag_f32_e32 v4, v4
	v_add_u32_e32 v5, s4, v1
	v_mul_f32_e32 v4, 0x4f7ffffe, v4
	v_cvt_u32_f32_e32 v4, v4
	v_mul_lo_u32 v1, v3, v4
	v_mul_hi_u32 v1, v4, v1
	v_add_u32_e32 v1, v4, v1
	v_mul_hi_u32 v1, v5, v1
	v_mul_lo_u32 v3, v1, v2
	v_sub_u32_e32 v3, v5, v3
	v_add_u32_e32 v4, 1, v1
	v_cmp_ge_u32_e32 vcc, v3, v2
	s_nop 1
	v_cndmask_b32_e32 v1, v1, v4, vcc
	v_sub_u32_e32 v4, v3, v2
	v_cndmask_b32_e32 v3, v3, v4, vcc
	v_add_u32_e32 v4, 1, v1
	v_cmp_ge_u32_e32 vcc, v3, v2
	v_add_u32_e32 v3, 1, v5
	s_nop 0
	v_cndmask_b32_e32 v1, v1, v4, vcc
	v_mul_lo_u32 v4, v2, v1
	v_add_u32_e32 v2, v4, v2
	v_cmp_ne_u32_e32 vcc, v3, v2
	s_and_saveexec_b64 s[6:7], vcc
	s_xor_b64 s[6:7], exec, s[6:7]
	s_cbranch_execz .LBB0_1280
	v_readlane_b32 s8, v254, 28
	v_readlane_b32 s9, v254, 29
	s_waitcnt lgkmcnt(0)
	s_nop 3
	global_load_dword v0, v181, s[8:9] sc1
	s_waitcnt vmcnt(0)
	v_cmp_eq_u32_e32 vcc, v0, v1
	s_and_saveexec_b64 s[8:9], vcc
	s_cbranch_execz .LBB0_1279
	s_mov_b32 s4, 1
	s_mov_b64 s[10:11], 0
	s_branch .LBB0_1270
